# layer-0 w_out transposes moved out of the HBM-bound prep phase into mix(l=0) (needed only by GEMM2(l=0)); w_out transpose item now addresses layer l
# speedup vs baseline: 1.0075x; 1.0012x over previous
.LBB0_25:
	s_or_b64 exec, exec, s[6:7]
	v_mov_b32_e32 v0, s3
	s_waitcnt lgkmcnt(0)
	s_barrier
	ds_read_b32 v0, v0
	s_movk_i32 s6, 0x3df
	s_waitcnt lgkmcnt(0)
	v_cmp_lt_i32_e32 vcc, s6, v0
	v_readfirstlane_b32 s8, v0
	s_mov_b64 s[6:7], -1
	s_cbranch_vccnz .LBB0_20
	s_cmpk_gt_u32 s8, 0x29f
	s_cselect_b32 s100, 0x80, 0
	s_add_i32 s8, s8, s100
	s_lshl_b32 s46, s8, 1
	s_add_i32 s3, s46, s94
	s_cmpk_gt_i32 s3, 0xbf
	s_cbranch_scc0 .LBB0_349
	s_cmpk_gt_u32 s3, 0x1ff
	s_cbranch_scc0 .LBB0_49
	s_cmpk_gt_u32 s3, 0x53f
	s_cbranch_scc0 .LBB0_46
	s_cmpk_gt_u32 s3, 0x63f
	s_cbranch_scc0 .LBB0_43
	s_cmpk_gt_u32 s3, 0x6bf
	s_cbranch_scc0 .LBB0_32
	s_cmpk_lt_u32 s3, 0x7c0
	s_mov_b32 s6, 0xf7a0000
	s_cselect_b32 s6, s6, 0xfba0000
	s_cselect_b32 s9, s69, s71
	s_cselect_b32 s8, s68, s70
	s_add_u32 s6, s30, s6
	s_addc_u32 s7, s31, 0
	s_lshl_b32 s10, s3, 13
	s_add_i32 s10, s10, 0x80000
	s_and_b32 s10, s10, 0x1fe000
	v_or_b32_e32 v8, s10, v70
	v_lshlrev_b32_e32 v4, 2, v8
	global_load_dwordx4 v[0:3], v4, s[8:9] offset:16
	s_nop 0
	global_load_dwordx4 v[4:7], v4, s[8:9]
	s_mov_b32 s10, 0x7060302
	v_lshlrev_b32_e32 v9, 1, v8
	v_or_b32_e32 v10, 0x800, v8
	v_lshlrev_b32_e32 v11, 2, v10
	v_lshlrev_b32_e32 v10, 1, v10
	s_waitcnt vmcnt(1)
	v_bfe_u32 v12, v3, 16, 1
	v_bfe_u32 v13, v2, 16, 1
	v_bfe_u32 v14, v1, 16, 1
	v_bfe_u32 v15, v0, 16, 1
	s_waitcnt vmcnt(0)
	v_bfe_u32 v16, v7, 16, 1
	v_bfe_u32 v17, v6, 16, 1
	v_bfe_u32 v18, v5, 16, 1
	v_bfe_u32 v19, v4, 16, 1
	v_add3_u32 v4, v4, v19, s95
	v_add3_u32 v5, v5, v18, s95
	v_add3_u32 v6, v6, v17, s95
	v_add3_u32 v7, v7, v16, s95
	v_add3_u32 v0, v0, v15, s95
	v_add3_u32 v1, v1, v14, s95
	v_add3_u32 v2, v2, v13, s95
	v_add3_u32 v3, v3, v12, s95
	v_perm_b32 v3, v3, v2, s10
	v_perm_b32 v2, v1, v0, s10
	v_perm_b32 v1, v7, v6, s10
	v_perm_b32 v0, v5, v4, s10
	global_store_dwordx4 v9, v[0:3], s[6:7]
	global_load_dwordx4 v[0:3], v11, s[8:9] offset:16
	s_nop 0
	global_load_dwordx4 v[4:7], v11, s[8:9]
	v_or_b32_e32 v9, 0x1000, v8
	v_lshlrev_b32_e32 v11, 2, v9
	v_or_b32_e32 v8, 0x1800, v8
	v_lshlrev_b32_e32 v9, 1, v9
	s_waitcnt vmcnt(1)
	v_bfe_u32 v12, v3, 16, 1
	v_bfe_u32 v13, v2, 16, 1
	v_bfe_u32 v14, v1, 16, 1
	v_bfe_u32 v15, v0, 16, 1
	s_waitcnt vmcnt(0)
	v_bfe_u32 v16, v7, 16, 1
	v_bfe_u32 v17, v6, 16, 1
	v_bfe_u32 v18, v5, 16, 1
	v_bfe_u32 v19, v4, 16, 1
	v_add3_u32 v4, v4, v19, s95
	v_add3_u32 v5, v5, v18, s95
	v_add3_u32 v6, v6, v17, s95
	v_add3_u32 v7, v7, v16, s95
	v_add3_u32 v0, v0, v15, s95
	v_add3_u32 v1, v1, v14, s95
	v_add3_u32 v2, v2, v13, s95
	v_add3_u32 v3, v3, v12, s95
	v_perm_b32 v3, v3, v2, s10
	v_perm_b32 v2, v1, v0, s10
	v_perm_b32 v1, v7, v6, s10
	v_perm_b32 v0, v5, v4, s10
	global_store_dwordx4 v10, v[0:3], s[6:7]
	global_load_dwordx4 v[0:3], v11, s[8:9] offset:16
	s_nop 0
	global_load_dwordx4 v[4:7], v11, s[8:9]
	v_lshlrev_b32_e32 v10, 2, v8
	v_lshlrev_b32_e32 v8, 1, v8
	s_waitcnt vmcnt(1)
	v_bfe_u32 v11, v3, 16, 1
	v_bfe_u32 v12, v2, 16, 1
	v_bfe_u32 v13, v1, 16, 1
	v_bfe_u32 v14, v0, 16, 1
	s_waitcnt vmcnt(0)
	v_bfe_u32 v15, v7, 16, 1
	v_bfe_u32 v16, v6, 16, 1
	v_bfe_u32 v17, v5, 16, 1
	v_bfe_u32 v18, v4, 16, 1
	v_add3_u32 v4, v4, v18, s95
	v_add3_u32 v5, v5, v17, s95
	v_add3_u32 v6, v6, v16, s95
	v_add3_u32 v7, v7, v15, s95
	v_add3_u32 v0, v0, v14, s95
	v_add3_u32 v1, v1, v13, s95
	v_add3_u32 v2, v2, v12, s95
	v_add3_u32 v3, v3, v11, s95
	v_perm_b32 v3, v3, v2, s10
	v_perm_b32 v2, v1, v0, s10
	v_perm_b32 v1, v7, v6, s10
	v_perm_b32 v0, v5, v4, s10
	global_store_dwordx4 v9, v[0:3], s[6:7]
	global_load_dwordx4 v[0:3], v10, s[8:9] offset:16
	s_nop 0
	global_load_dwordx4 v[4:7], v10, s[8:9]
	s_waitcnt vmcnt(1)
	v_bfe_u32 v9, v3, 16, 1
	v_bfe_u32 v10, v2, 16, 1
	v_bfe_u32 v11, v1, 16, 1
	v_bfe_u32 v12, v0, 16, 1
	s_waitcnt vmcnt(0)
	v_bfe_u32 v13, v7, 16, 1
	v_bfe_u32 v14, v6, 16, 1
	v_bfe_u32 v15, v5, 16, 1
	v_bfe_u32 v16, v4, 16, 1
	v_add3_u32 v4, v4, v16, s95
	v_add3_u32 v5, v5, v15, s95
	v_add3_u32 v6, v6, v14, s95
	v_add3_u32 v7, v7, v13, s95
	v_add3_u32 v0, v0, v12, s95
	v_add3_u32 v1, v1, v11, s95
	v_add3_u32 v2, v2, v10, s95
	v_add3_u32 v3, v3, v9, s95
	v_perm_b32 v3, v3, v2, s10
	v_perm_b32 v2, v1, v0, s10
	v_perm_b32 v1, v7, v6, s10
	v_perm_b32 v0, v5, v4, s10
	global_store_dwordx4 v8, v[0:3], s[6:7]
	s_mov_b64 s[6:7], 0

.LBB0_633:
	s_or_b64 exec, exec, s[36:37]
	s_lshl_b32 s70, s14, 6
	s_lshl_b64 s[20:21], s[70:71], 2
	s_add_u32 s15, s30, s20
	s_addc_u32 s16, s31, s21
	s_add_u32 s20, s15, 0xf79f700
	s_waitcnt lgkmcnt(0)
	v_cvt_f32_u32_e32 v0, s14
	s_addc_u32 s21, s16, 0
	s_and_b32 s100, s2, 7
	s_nop 0
	s_lshl_b32 s101, s100, 5
	s_add_u32 s20, s20, s101
	s_addc_u32 s21, s21, 0
	v_writelane_b32 v254, s100, 0
	s_lshr_b32 s101, s2, 3
	s_add_i32 s101, s101, 1
	v_writelane_b32 v254, s101, 1
	v_writelane_b32 v251, s20, 37
	v_writelane_b32 v253, s84, 10
	s_movk_i32 s15, 0xbc
	v_writelane_b32 v251, s21, 38
	s_and_b64 s[20:21], s[84:85], exec
	s_cselect_b32 s15, s15, 0x88
	s_movk_i32 s100, 68
	s_cselect_b32 s100, s100, 16
	s_movk_i32 s101, 0x4e8
	s_cselect_b32 s101, 0x348, s101
	v_writelane_b32 v254, s100, 2
	v_writelane_b32 v254, s101, 3
	s_lshl_b32 s100, s14, 24
	v_readlane_b32 s101, v253, 0
	s_nop 0
	s_add_u32 s100, s101, s100
	v_readlane_b32 s101, v253, 1
	s_nop 0
	s_addc_u32 s101, s101, 0
	v_writelane_b32 v252, s100, 45
	v_writelane_b32 v252, s101, 46
	s_lshl_b32 s100, s14, 23
	s_add_u32 s100, s100, 0x3400000
	s_add_u32 s100, s30, s100
	s_addc_u32 s101, s31, 0
	v_writelane_b32 v252, s100, 47
	v_writelane_b32 v252, s101, 48
	s_lshl_b32 s16, s14, 16
	v_mul_f32_e32 v0, 0xbe99999a, v0
	v_writelane_b32 v251, s16, 39
	v_mul_f32_e32 v1, 0x3fb8aa3b, v0
	s_mov_b32 s16, 0x3fb8aa3b
	v_fma_f32 v2, v0, s16, -v1
	v_rndne_f32_e32 v3, v1
	v_fmac_f32_e32 v2, 0x32a5705f, v0
	v_sub_f32_e32 v1, v1, v3
	v_add_f32_e32 v1, v1, v2
	v_exp_f32_e32 v1, v1
	v_cvt_i32_f32_e32 v2, v3
	s_lshl_b32 s16, s14, 2
	v_writelane_b32 v251, s16, 40
	s_mov_b32 s16, 0xc2ce8ed0
	v_ldexp_f32 v1, v1, v2
	v_cmp_ngt_f32_e32 vcc, s16, v0
	s_mov_b32 s16, 0x42b17218
	s_lshl_b32 s38, s14, 9
	v_cndmask_b32_e32 v1, 0, v1, vcc
	v_cmp_nlt_f32_e32 vcc, s16, v0
	s_lshl_b32 s16, s14, 7
	v_writelane_b32 v251, s16, 41
	s_lshl_b32 s19, s14, 18
	v_writelane_b32 v251, s19, 42
	s_mov_b32 s40, s38
	v_writelane_b32 v253, s85, 11
	v_writelane_b32 v251, s40, 43
	s_mov_b32 s39, s71
	s_lshl_b32 s74, s14, 10
	v_writelane_b32 v251, s41, 44
	v_readlane_b32 s40, v253, 12
	s_lshl_b32 s70, s14, 8
	s_or_b32 s16, s74, 0x200
	s_lshl_b32 s36, s14, 6
	s_lshl_b64 s[38:39], s[38:39], 2
	v_readlane_b32 s48, v253, 20
	v_readlane_b32 s49, v253, 21
	s_add_u32 s19, s48, s38
	v_readlane_b32 s50, v253, 22
	v_writelane_b32 v251, s19, 45
	s_addc_u32 s19, s49, s39
	s_lshl_b64 s[38:39], s[70:71], 2
	s_mul_i32 s20, s14, 0x1200
	s_mov_b32 s21, s71
	v_readlane_b32 s51, v253, 23
	s_add_u32 s38, s50, s38
	v_readlane_b32 s54, v253, 26
	s_addc_u32 s39, s51, s39
	s_lshl_b64 s[20:21], s[20:21], 2
	s_mul_i32 s22, s14, 0x600
	s_mov_b32 s23, s71
	v_readlane_b32 s55, v253, 27
	s_add_u32 s80, s54, s20
	s_addc_u32 s81, s55, s21
	s_lshl_b64 s[20:21], s[22:23], 2
	s_mov_b32 s37, s71
	v_writelane_b32 v251, s19, 46
	s_add_u32 s82, s12, s20
	v_writelane_b32 v251, s38, 47
	s_addc_u32 s83, s13, s21
	s_lshl_b64 s[20:21], s[36:37], 2
	v_readlane_b32 s19, v252, 53
	v_writelane_b32 v251, s39, 48
	s_add_u32 s19, s19, s20
	v_writelane_b32 v251, s19, 49
	v_readlane_b32 s19, v252, 54
	s_addc_u32 s19, s19, s21
	s_add_u32 s17, s17, 0x1800000
	v_writelane_b32 v251, s19, 50
	v_writelane_b32 v251, s17, 51
	s_addc_u32 s17, s18, 0
	v_writelane_b32 v251, s17, 52
	v_readfirstlane_b32 s17, v188
	s_lshr_b32 s18, s17, 8
	s_mul_i32 s17, s18, 0x12000
	s_add_i32 s17, s17, 0
	v_writelane_b32 v251, s18, 53
	s_addk_i32 s18, 0xff80
	v_writelane_b32 v251, s18, 54
	s_add_i32 s18, s17, 0x8800
	v_writelane_b32 v251, s18, 55
	s_add_i32 s18, s17, 0x4400
	v_writelane_b32 v251, s18, 56
	s_add_i32 s18, s17, 0x800
	v_writelane_b32 v251, s18, 57
	s_mul_i32 s19, s14, 0x1a00000
	v_readlane_b32 s20, v251, 32
	s_add_u32 s19, s20, s19
	v_cndmask_b32_e32 v0, v200, v1, vcc
	v_writelane_b32 v251, s19, 58
	v_fmamk_f32 v150, v0, 0xbf19999a, v192
	s_mul_hi_u32 s18, s14, 0x1a00000
	v_readlane_b32 s19, v251, 33
	v_sub_f32_e32 v203, 1.0, v150
	s_mov_b32 s75, s71
	s_addc_u32 s18, s19, s18
	s_barrier
	v_readlane_b32 s41, v253, 13
	v_readlane_b32 s42, v253, 14
	v_readlane_b32 s43, v253, 15
	v_readlane_b32 s44, v253, 16
	v_readlane_b32 s45, v253, 17
	v_readlane_b32 s46, v253, 18
	v_readlane_b32 s47, v253, 19
	v_readlane_b32 s52, v253, 24
	v_readlane_b32 s53, v253, 25
	v_writelane_b32 v251, s18, 59
	s_branch .LBB0_637
